# conv taps (62 KB) LDS-DMA'd by waves 1-7 inside grid barrier 2 instead of VGPR-staged after it
# baseline (speedup 1.0000x reference)
.LBB0_292:
	s_waitcnt vmcnt(0)
	s_and_b64 vcc, exec, s[28:29]
	s_waitcnt vmcnt(0)
	s_barrier
	s_cmp_lt_u32 s94, 64
	s_cbranch_scc1 .Ltaps_done
	s_lshr_b32 s98, s94, 6
	s_add_i32 s98, s98, -1
	s_lshl_b32 s98, s98, 10
	s_mov_b32 s99, 0
	v_mbcnt_lo_u32_b32 v248, -1, 0
	v_mbcnt_hi_u32_b32 v248, -1, v248
	v_lshlrev_b32_e32 v248, 4, v248
	v_mov_b32_e32 v249, 0
	v_lshl_add_u64 v[250:251], s[62:63], 0, v[248:249]
.Ltaps_loop:
	s_mov_b32 m0, s98
	v_lshl_add_u64 v[252:253], v[250:251], 0, s[98:99]
	global_load_lds_dwordx4 v[252:253], off
	s_add_i32 s98, s98, 0x1c00
	s_cmp_lt_u32 s98, 0xf800
	s_cbranch_scc1 .Ltaps_loop
	s_waitcnt vmcnt(0)
.Ltaps_done:
	s_cbranch_vccnz .LBB0_346
	v_mbcnt_lo_u32_b32 v0, -1, 0
	v_mbcnt_hi_u32_b32 v0, -1, v0
	s_nop 0
	v_cmp_eq_u32_e32 vcc, 0, v0
	s_and_saveexec_b64 s[2:3], vcc
	s_cbranch_execz .LBB0_345
	s_add_i32 s0, 0, 0x20160
	v_mov_b32_e32 v0, s0
	s_waitcnt vmcnt(0) expcnt(0) lgkmcnt(0)
	ds_read_b32 v2, v0
	s_add_i32 s0, 0, 0x20164
	v_mov_b32_e32 v0, s0
	ds_read_b32 v0, v0
	s_waitcnt lgkmcnt(1)
	v_cmp_ne_u32_e32 vcc, 0, v2
	s_cbranch_vccnz .LBB0_309
	v_readlane_b32 s4, v247, 8
	v_readlane_b32 s5, v247, 9
	s_load_dwordx2 s[0:1], s[4:5], 0x4
	s_add_u32 s4, s92, 0x1200
	s_addc_u32 s5, s93, 0
	s_add_u32 s6, s92, 0x1400
	s_addc_u32 s7, s93, 0
	v_readlane_b32 s8, v247, 10
	s_waitcnt lgkmcnt(0)
	s_mul_i32 s0, s0, s8
	s_add_u32 s8, s92, 0x1500
	s_addc_u32 s9, s93, 0
	s_add_u32 s12, s92, 0x1600
	s_addc_u32 s13, s93, 0
	s_add_u32 s14, s92, 0x1700
	s_addc_u32 s15, s93, 0
	s_add_u32 s16, s92, 0x1800
	s_addc_u32 s17, s93, 0
	s_add_u32 s18, s92, 0x1900
	s_addc_u32 s19, s93, 0
	s_add_u32 s20, s92, 0x1a00
	s_addc_u32 s21, s93, 0
	s_add_u32 s22, s92, 0x1b00
	s_addc_u32 s23, s93, 0
	s_add_u32 s30, s92, 0x1c00
	s_addc_u32 s31, s93, 0
	s_add_u32 s34, s92, 0x1d00
	s_addc_u32 s35, s93, 0
	s_add_u32 s44, s92, 0x1e00
	s_addc_u32 s45, s93, 0
	s_add_u32 s50, s92, 0x1f00
	s_addc_u32 s51, s93, 0
	s_add_u32 s68, s92, 0x2000
	s_addc_u32 s69, s93, 0
	s_add_u32 s70, s92, 0x2100
	s_addc_u32 s71, s93, 0
	s_add_u32 s72, s92, 0x2200
	s_addc_u32 s73, s93, 0
	s_add_u32 s74, s92, 0x2300
	s_mul_i32 s0, s0, s1
	s_addc_u32 s75, s93, 0
	s_mov_b32 s1, 1
	v_mov_b32_e32 v16, 0
	s_branch .LBB0_297

.LBB0_346:
	s_waitcnt lgkmcnt(0)
	s_barrier
	v_mbcnt_lo_u32_b32 v0, -1, 0
	v_mbcnt_hi_u32_b32 v0, -1, v0
	s_movk_i32 s0, 0
	v_add_u32_e32 v0, s94, v0
	s_nop 0
	v_readfirstlane_b32 s1, v0
	v_cmp_gt_i32_e32 vcc, s0, v0
	s_and_saveexec_b64 s[2:3], vcc
	s_cbranch_execz .LBB0_359
	v_max_i32_e32 v1, 0x3c00, v0
	v_sub_u32_e32 v1, v1, v0
	s_movk_i32 s0, 0x1ff
	v_add_u32_e32 v1, 0x1ff, v1
	v_cmp_lt_u32_e32 vcc, s0, v1
	s_mov_b64 s[6:7], -1
	v_mov_b32_e32 v2, v0
	s_and_saveexec_b64 s[4:5], vcc
	s_cbranch_execz .LBB0_356
	v_lshrrev_b32_e32 v4, 9, v1
	v_add_u32_e32 v2, -1, v4
	v_add_u32_e32 v1, 0x200, v0
	v_lshrrev_b32_e32 v3, 1, v2
	v_add_u32_e32 v5, 1, v3
	v_cmp_lt_u32_e32 vcc, 13, v2
	v_mov_b32_e32 v8, 0
	v_mov_b64_e32 v[2:3], v[0:1]
	s_and_saveexec_b64 s[6:7], vcc
	s_cbranch_execz .LBB0_352
	v_and_b32_e32 v6, -8, v5
	s_mov_b32 s0, 0
	v_lshl_add_u32 v7, v0, 2, 0
	s_mov_b64 s[8:9], 0
	v_mov_b64_e32 v[2:3], v[0:1]

	.amdhsa_kernel _Z9hymba_fwd4Args
		.amdhsa_group_segment_fixed_size 0
		.amdhsa_private_segment_fixed_size 0
		.amdhsa_kernarg_size 440
		.amdhsa_user_sgpr_count 2
		.amdhsa_user_sgpr_dispatch_ptr 0
		.amdhsa_user_sgpr_queue_ptr 0
		.amdhsa_user_sgpr_kernarg_segment_ptr 1
		.amdhsa_user_sgpr_dispatch_id 0
		.amdhsa_user_sgpr_kernarg_preload_length 0
		.amdhsa_user_sgpr_kernarg_preload_offset 0
		.amdhsa_user_sgpr_private_segment_size 0
		.amdhsa_uses_dynamic_stack 0
		.amdhsa_enable_private_segment 0
		.amdhsa_system_sgpr_workgroup_id_x 1
		.amdhsa_system_sgpr_workgroup_id_y 0
		.amdhsa_system_sgpr_workgroup_id_z 0
		.amdhsa_system_sgpr_workgroup_info 0
		.amdhsa_system_vgpr_workitem_id 0
		.amdhsa_next_free_vgpr 256
		.amdhsa_next_free_sgpr 102
		.amdhsa_accum_offset 256
		.amdhsa_reserve_vcc 1
		.amdhsa_float_round_mode_32 0
		.amdhsa_float_round_mode_16_64 0
		.amdhsa_float_denorm_mode_32 3
		.amdhsa_float_denorm_mode_16_64 3
		.amdhsa_dx10_clamp 1
		.amdhsa_ieee_mode 1
		.amdhsa_fp16_overflow 0
		.amdhsa_tg_split 0
		.amdhsa_exception_fp_ieee_invalid_op 0
		.amdhsa_exception_fp_denorm_src 0
		.amdhsa_exception_fp_ieee_div_zero 0
		.amdhsa_exception_fp_ieee_overflow 0
		.amdhsa_exception_fp_ieee_underflow 0
		.amdhsa_exception_fp_ieee_inexact 0
		.amdhsa_exception_int_div_zero 0
	.end_amdhsa_kernel

amdhsa.kernels:
  - .agpr_count:     0
    .args:
      - .offset:         0
        .size:           184
        .value_kind:     by_value
      - .offset:         184
        .size:           4
        .value_kind:     hidden_block_count_x
      - .offset:         188
        .size:           4
        .value_kind:     hidden_block_count_y
      - .offset:         192
        .size:           4
        .value_kind:     hidden_block_count_z
      - .offset:         196
        .size:           2
        .value_kind:     hidden_group_size_x
      - .offset:         198
        .size:           2
        .value_kind:     hidden_group_size_y
      - .offset:         200
        .size:           2
        .value_kind:     hidden_group_size_z
      - .offset:         202
        .size:           2
        .value_kind:     hidden_remainder_x
      - .offset:         204
        .size:           2
        .value_kind:     hidden_remainder_y
      - .offset:         206
        .size:           2
        .value_kind:     hidden_remainder_z
      - .offset:         224
        .size:           8
        .value_kind:     hidden_global_offset_x
      - .offset:         232
        .size:           8
        .value_kind:     hidden_global_offset_y
      - .offset:         240
        .size:           8
        .value_kind:     hidden_global_offset_z
      - .offset:         248
        .size:           2
        .value_kind:     hidden_grid_dims
      - .offset:         304
        .size:           4
        .value_kind:     hidden_dynamic_lds_size
    .group_segment_fixed_size: 0
    .kernarg_segment_align: 8
    .kernarg_segment_size: 440
    .language:       OpenCL C
    .language_version:
      - 2
      - 0
    .max_flat_workgroup_size: 512
    .name:           _Z9hymba_fwd4Args
    .private_segment_fixed_size: 0
    .sgpr_count:     108
    .sgpr_spill_count: 65
    .symbol:         _Z9hymba_fwd4Args.kd
    .uniform_work_group_size: 1
    .uses_dynamic_stack: false
    .vgpr_count:     256
    .vgpr_spill_count: 0
    .wavefront_size: 64
